# nt (streaming) hint on the f32 residual-stream stores of the w_out and ffn-out GEMM epilogues
# speedup vs baseline: 1.0099x; 1.0071x over previous
.LBB0_1040:
	s_lshl_b32 s45, s58, 8
	s_add_i32 s45, s45, s59
	s_ashr_i32 s12, s45, 13
	s_mulk_i32 s12, 0x1800
	v_or_b32_e32 v154, s45, v162
	s_ashr_i32 s13, s12, 31
	v_lshl_or_b32 v144, s56, 8, v164
	v_ashrrev_i32_e32 v155, 31, v154
	s_lshl_b64 s[12:13], s[12:13], 2
	v_ashrrev_i32_e32 v145, 31, v144
	v_lshlrev_b64 v[146:147], 10, v[154:155]
	s_add_u32 s12, s68, s12
	v_lshl_add_u64 v[158:159], v[146:147], 0, v[144:145]
	s_addc_u32 s13, s69, s13
	v_readlane_b32 s76, v250, 6
	v_lshl_add_u64 v[156:157], v[144:145], 2, s[12:13]
	v_lshlrev_b64 v[146:147], 2, v[158:159]
	v_readlane_b32 s77, v250, 7
	v_add_co_u32_e32 v152, vcc, s47, v156
	s_nop 0
	v_lshl_add_u64 v[150:151], s[76:77], 0, v[146:147]
	global_load_dwordx4 v[170:173], v[150:151], off offset:16
	global_load_dwordx4 v[174:177], v[150:151], off
	v_addc_co_u32_e32 v153, vcc, 0, v157, vcc
	v_lshl_add_u64 v[148:149], v[156:157], 0, s[22:23]
	global_load_dwordx4 v[178:181], v[152:153], off
	global_load_dwordx4 v[182:185], v[148:149], off offset:16
	global_load_dwordx4 v[186:189], v[150:151], off offset:528
	global_load_dwordx4 v[190:193], v[150:151], off offset:512
	global_load_dwordx4 v[198:201], v[152:153], off offset:512
	v_lshl_add_u64 v[150:151], v[156:157], 0, s[24:25]
	global_load_dwordx4 v[202:205], v[150:151], off offset:16
	v_and_b32_e32 v153, 64, v168
	v_xor_b32_e32 v152, 16, v168
	v_add_u32_e32 v195, 64, v153
	v_cmp_lt_i32_e32 vcc, v152, v195
	v_xor_b32_e32 v194, 32, v168
	v_readlane_b32 s78, v250, 8
	v_cndmask_b32_e32 v152, v168, v152, vcc
	v_lshlrev_b32_e32 v169, 2, v152
	v_cmp_lt_i32_e32 vcc, v194, v195
	v_readlane_b32 s79, v250, 9
	v_readlane_b32 s80, v250, 10
	v_readlane_b32 s81, v250, 11
	v_readlane_b32 s82, v250, 12
	v_readlane_b32 s83, v250, 13
	v_readlane_b32 s84, v250, 14
	v_readlane_b32 s85, v250, 15
	v_readlane_b32 s86, v250, 16
	v_readlane_b32 s87, v250, 17
	v_readlane_b32 s88, v250, 18
	v_readlane_b32 s89, v250, 19
	v_readlane_b32 s90, v250, 20
	v_readlane_b32 s91, v250, 21
	s_waitcnt vmcnt(0)
	v_pk_fma_f32 v[126:127], v[126:127], v[180:181], v[176:177]
	v_pk_fma_f32 v[122:123], v[122:123], v[184:185], v[172:173]
	v_pk_fma_f32 v[120:121], v[120:121], v[182:183], v[170:171]
	v_pk_fma_f32 v[124:125], v[124:125], v[178:179], v[174:175]
	v_pk_mul_f32 v[152:153], v[122:123], v[122:123]
	v_pk_mul_f32 v[160:161], v[120:121], v[120:121]
	v_pk_fma_f32 v[118:119], v[118:119], v[200:201], v[192:193]
	v_pk_fma_f32 v[116:117], v[116:117], v[198:199], v[190:191]
	v_pk_fma_f32 v[152:153], v[126:127], v[126:127], v[152:153]
	v_pk_fma_f32 v[160:161], v[124:125], v[124:125], v[160:161]
	v_pk_fma_f32 v[114:115], v[114:115], v[204:205], v[188:189]
	v_pk_fma_f32 v[112:113], v[112:113], v[202:203], v[186:187]
	v_pk_fma_f32 v[152:153], v[118:119], v[118:119], v[152:153]
	v_pk_fma_f32 v[160:161], v[116:117], v[116:117], v[160:161]
	v_pk_fma_f32 v[152:153], v[114:115], v[114:115], v[152:153]
	v_pk_fma_f32 v[160:161], v[112:113], v[112:113], v[160:161]
	v_add_f32_e32 v152, v152, v153
	v_add_f32_e32 v160, v160, v161
	v_add_f32_e32 v160, v160, v152
	ds_bpermute_b32 v161, v169, v160
	v_cndmask_b32_e32 v152, v168, v194, vcc
	v_lshlrev_b32_e32 v170, 2, v152
	v_lshl_add_u64 v[152:153], s[30:31], 0, v[146:147]
	global_store_dwordx4 v[152:153], v[124:127], off nt
	global_store_dwordx4 v[152:153], v[120:123], off offset:16 nt
	global_store_dwordx4 v[152:153], v[116:119], off offset:512 nt
	global_store_dwordx4 v[152:153], v[112:115], off offset:528 nt
	s_waitcnt lgkmcnt(0)
	v_add_f32_e32 v146, v160, v161
	ds_bpermute_b32 v147, v170, v146
	s_and_saveexec_b64 s[12:13], s[0:1]
	s_cbranch_execz .LBB0_1042
	v_lshl_add_u64 v[152:153], v[154:155], 2, s[8:9]
	s_waitcnt lgkmcnt(0)
	v_add_f32_e32 v146, v146, v147
	global_atomic_add_f32 v[152:153], v146, off
.LBB0_1042:
	s_or_b64 exec, exec, s[12:13]
	v_readlane_b32 s76, v250, 6
	v_readlane_b32 s90, v250, 20
	v_readlane_b32 s91, v250, 21
	s_mov_b64 s[50:51], s[90:91]
	v_add_co_u32_e32 v160, vcc, 0x4000, v156
	v_lshl_add_u64 v[152:153], v[156:157], 0, s[26:27]
	s_waitcnt lgkmcnt(0)
	v_lshl_add_u64 v[146:147], v[144:145], 2, s[50:51]
	v_addc_co_u32_e32 v161, vcc, 0, v157, vcc
	v_lshl_add_u64 v[156:157], v[156:157], 0, s[28:29]
	global_load_dwordx4 v[172:175], v[152:153], off offset:16
	global_load_dwordx4 v[176:179], v[146:147], off offset:16
	global_load_dwordx4 v[180:183], v[146:147], off
	global_load_dwordx4 v[184:187], v[146:147], off offset:528
	global_load_dwordx4 v[188:191], v[146:147], off offset:512
	global_load_dwordx4 v[192:195], v[160:161], off
	global_load_dwordx4 v[198:201], v[160:161], off offset:512
	global_load_dwordx4 v[202:205], v[156:157], off offset:16
	v_or_b32_e32 v160, 16, v154
	v_ashrrev_i32_e32 v161, 31, v160
	v_lshl_add_u64 v[206:207], v[158:159], 1, s[34:35]
	v_lshlrev_b64 v[158:159], 10, v[160:161]
	v_readlane_b32 s77, v250, 7
	v_lshl_add_u64 v[158:159], v[158:159], 0, v[144:145]
	s_mov_b64 s[36:37], s[76:77]
	v_lshlrev_b64 v[208:209], 2, v[158:159]
	v_lshl_add_u64 v[210:211], s[36:37], 0, v[208:209]
	v_readlane_b32 s78, v250, 8
	v_readlane_b32 s79, v250, 9
	v_readlane_b32 s80, v250, 10
	v_readlane_b32 s81, v250, 11
	v_readlane_b32 s82, v250, 12
	v_readlane_b32 s83, v250, 13
	v_readlane_b32 s84, v250, 14
	v_readlane_b32 s85, v250, 15
	v_readlane_b32 s86, v250, 16
	v_readlane_b32 s87, v250, 17
	v_readlane_b32 s88, v250, 18
	v_readlane_b32 s89, v250, 19
	s_waitcnt vmcnt(7)
	v_pk_add_f32 v[174:175], v[174:175], 1.0 op_sel_hi:[1,0]
	v_pk_add_f32 v[172:173], v[172:173], 1.0 op_sel_hi:[1,0]
	s_waitcnt vmcnt(5)
	v_pk_mul_f32 v[126:127], v[126:127], v[182:183]
	v_pk_mul_f32 v[124:125], v[124:125], v[180:181]
	v_pk_mul_f32 v[122:123], v[122:123], v[178:179]
	v_pk_mul_f32 v[120:121], v[120:121], v[176:177]
	s_waitcnt vmcnt(4)
	v_pk_mul_f32 v[114:115], v[114:115], v[186:187]
	v_pk_mul_f32 v[112:113], v[112:113], v[184:185]
	s_waitcnt vmcnt(2)
	v_pk_add_f32 v[176:177], v[194:195], 1.0 op_sel_hi:[1,0]
	v_pk_add_f32 v[178:179], v[192:193], 1.0 op_sel_hi:[1,0]
	s_waitcnt vmcnt(0)
	v_pk_add_f32 v[184:185], v[204:205], 1.0 op_sel_hi:[1,0]
	v_pk_add_f32 v[186:187], v[202:203], 1.0 op_sel_hi:[1,0]
	v_pk_mul_f32 v[118:119], v[118:119], v[190:191]
	v_pk_mul_f32 v[116:117], v[116:117], v[188:189]
	v_pk_add_f32 v[180:181], v[200:201], 1.0 op_sel_hi:[1,0]
	v_pk_add_f32 v[182:183], v[198:199], 1.0 op_sel_hi:[1,0]
	v_pk_mul_f32 v[122:123], v[174:175], v[122:123]
	v_pk_mul_f32 v[120:121], v[172:173], v[120:121]
	v_pk_mul_f32 v[126:127], v[176:177], v[126:127]
	v_pk_mul_f32 v[124:125], v[178:179], v[124:125]
	v_pk_mul_f32 v[172:173], v[184:185], v[114:115]
	v_pk_mul_f32 v[174:175], v[186:187], v[112:113]
	v_cvt_pk_bf16_f32 v112, v124, v125
	v_cvt_pk_bf16_f32 v113, v126, v127
	v_cvt_pk_bf16_f32 v114, v120, v121
	v_cvt_pk_bf16_f32 v115, v122, v123
	v_pk_mul_f32 v[118:119], v[180:181], v[118:119]
	v_pk_mul_f32 v[116:117], v[182:183], v[116:117]
	global_store_dwordx4 v[206:207], v[112:115], off
	s_nop 1
	v_cvt_pk_bf16_f32 v112, v116, v117
	v_cvt_pk_bf16_f32 v113, v118, v119
	v_cvt_pk_bf16_f32 v114, v174, v175
	v_cvt_pk_bf16_f32 v115, v172, v173
	global_store_dwordx4 v[206:207], v[112:115], off offset:256
	global_load_dwordx4 v[112:115], v[148:149], off
	s_nop 0
	global_load_dwordx4 v[116:119], v[210:211], off
	global_load_dwordx4 v[120:123], v[210:211], off offset:16
	global_load_dwordx4 v[124:127], v[148:149], off offset:16
	global_load_dwordx4 v[172:175], v[150:151], off
	global_load_dwordx4 v[176:179], v[210:211], off offset:512
	global_load_dwordx4 v[180:183], v[210:211], off offset:528
	global_load_dwordx4 v[184:187], v[150:151], off offset:16
	s_waitcnt vmcnt(6)
	v_pk_fma_f32 v[110:111], v[110:111], v[114:115], v[118:119]
	v_pk_fma_f32 v[108:109], v[108:109], v[112:113], v[116:117]
	s_waitcnt vmcnt(4)
	v_pk_fma_f32 v[106:107], v[106:107], v[126:127], v[122:123]
	v_pk_fma_f32 v[104:105], v[104:105], v[124:125], v[120:121]
	v_pk_mul_f32 v[112:113], v[106:107], v[106:107]
	v_pk_mul_f32 v[114:115], v[104:105], v[104:105]
	s_waitcnt vmcnt(2)
	v_pk_fma_f32 v[102:103], v[102:103], v[174:175], v[178:179]
	v_pk_fma_f32 v[100:101], v[100:101], v[172:173], v[176:177]
	v_pk_fma_f32 v[112:113], v[110:111], v[110:111], v[112:113]
	v_pk_fma_f32 v[114:115], v[108:109], v[108:109], v[114:115]
	s_waitcnt vmcnt(0)
	v_pk_fma_f32 v[98:99], v[98:99], v[186:187], v[182:183]
	v_pk_fma_f32 v[96:97], v[96:97], v[184:185], v[180:181]
	v_pk_fma_f32 v[112:113], v[102:103], v[102:103], v[112:113]
	v_pk_fma_f32 v[114:115], v[100:101], v[100:101], v[114:115]
	v_pk_fma_f32 v[112:113], v[98:99], v[98:99], v[112:113]
	v_pk_fma_f32 v[114:115], v[96:97], v[96:97], v[114:115]
	v_add_f32_e32 v112, v112, v113
	v_add_f32_e32 v114, v114, v115
	v_add_f32_e32 v112, v114, v112
	ds_bpermute_b32 v113, v169, v112
	v_lshl_add_u64 v[114:115], s[30:31], 0, v[208:209]
	global_store_dwordx4 v[114:115], v[108:111], off nt
	global_store_dwordx4 v[114:115], v[104:107], off offset:16 nt
	global_store_dwordx4 v[114:115], v[100:103], off offset:512 nt
	global_store_dwordx4 v[114:115], v[96:99], off offset:528 nt
	s_waitcnt lgkmcnt(0)
	v_add_f32_e32 v112, v112, v113
	ds_bpermute_b32 v113, v170, v112
	s_and_saveexec_b64 s[12:13], s[0:1]
	s_cbranch_execz .LBB0_1044
	v_lshl_add_u64 v[114:115], v[160:161], 2, s[8:9]
	s_waitcnt lgkmcnt(0)
	v_add_f32_e32 v112, v112, v113
	global_atomic_add_f32 v[114:115], v112, off
.LBB0_1044:
	s_or_b64 exec, exec, s[12:13]
	global_load_dwordx4 v[116:119], v[152:153], off
	global_load_dwordx4 v[120:123], v[152:153], off offset:16
	global_load_dwordx4 v[124:127], v[156:157], off
	global_load_dwordx4 v[172:175], v[156:157], off offset:16
	global_load_dwordx4 v[176:179], v[146:147], off
	global_load_dwordx4 v[180:183], v[146:147], off offset:16
	global_load_dwordx4 v[184:187], v[146:147], off offset:512
	global_load_dwordx4 v[188:191], v[146:147], off offset:528
	v_or_b32_e32 v114, 32, v154
	v_ashrrev_i32_e32 v115, 31, v114
	s_waitcnt lgkmcnt(0)
	v_lshlrev_b64 v[112:113], 10, v[114:115]
	v_lshl_add_u64 v[112:113], v[112:113], 0, v[144:145]
	v_readlane_b32 s76, v250, 6
	v_lshl_add_u64 v[158:159], v[158:159], 1, s[34:35]
	v_lshlrev_b64 v[192:193], 2, v[112:113]
	v_readlane_b32 s77, v250, 7
	v_readlane_b32 s78, v250, 8
	v_readlane_b32 s79, v250, 9
	v_lshl_add_u64 v[160:161], s[76:77], 0, v[192:193]
	v_readlane_b32 s80, v250, 10
	v_readlane_b32 s81, v250, 11
	v_readlane_b32 s82, v250, 12
	v_readlane_b32 s83, v250, 13
	v_readlane_b32 s84, v250, 14
	v_readlane_b32 s85, v250, 15
	v_readlane_b32 s86, v250, 16
	v_readlane_b32 s87, v250, 17
	v_readlane_b32 s88, v250, 18
	v_readlane_b32 s89, v250, 19
	v_readlane_b32 s90, v250, 20
	v_readlane_b32 s91, v250, 21
	s_waitcnt vmcnt(7)
	v_pk_add_f32 v[118:119], v[118:119], 1.0 op_sel_hi:[1,0]
	v_pk_add_f32 v[116:117], v[116:117], 1.0 op_sel_hi:[1,0]
	s_waitcnt vmcnt(6)
	v_pk_add_f32 v[122:123], v[122:123], 1.0 op_sel_hi:[1,0]
	v_pk_add_f32 v[120:121], v[120:121], 1.0 op_sel_hi:[1,0]
	s_waitcnt vmcnt(4)
	v_pk_add_f32 v[174:175], v[174:175], 1.0 op_sel_hi:[1,0]
	v_pk_add_f32 v[172:173], v[172:173], 1.0 op_sel_hi:[1,0]
	s_waitcnt vmcnt(3)
	v_pk_mul_f32 v[110:111], v[110:111], v[178:179]
	v_pk_mul_f32 v[108:109], v[108:109], v[176:177]
	s_waitcnt vmcnt(2)
	v_pk_mul_f32 v[106:107], v[106:107], v[182:183]
	v_pk_mul_f32 v[104:105], v[104:105], v[180:181]
	s_waitcnt vmcnt(0)
	v_pk_mul_f32 v[98:99], v[98:99], v[190:191]
	v_pk_mul_f32 v[96:97], v[96:97], v[188:189]
	v_pk_add_f32 v[126:127], v[126:127], 1.0 op_sel_hi:[1,0]
	v_pk_add_f32 v[124:125], v[124:125], 1.0 op_sel_hi:[1,0]
	v_pk_mul_f32 v[102:103], v[102:103], v[186:187]
	v_pk_mul_f32 v[100:101], v[100:101], v[184:185]
	v_pk_mul_f32 v[110:111], v[118:119], v[110:111]
	v_pk_mul_f32 v[108:109], v[116:117], v[108:109]
	v_pk_mul_f32 v[106:107], v[122:123], v[106:107]
	v_pk_mul_f32 v[104:105], v[120:121], v[104:105]
	v_pk_mul_f32 v[116:117], v[174:175], v[98:99]
	v_pk_mul_f32 v[118:119], v[172:173], v[96:97]
	v_cvt_pk_bf16_f32 v96, v108, v109
	v_cvt_pk_bf16_f32 v97, v110, v111
	v_cvt_pk_bf16_f32 v98, v104, v105
	v_cvt_pk_bf16_f32 v99, v106, v107
	v_pk_mul_f32 v[102:103], v[126:127], v[102:103]
	v_pk_mul_f32 v[100:101], v[124:125], v[100:101]
	global_store_dwordx4 v[158:159], v[96:99], off
	s_nop 1
	v_cvt_pk_bf16_f32 v96, v100, v101
	v_cvt_pk_bf16_f32 v97, v102, v103
	v_cvt_pk_bf16_f32 v98, v118, v119
	v_cvt_pk_bf16_f32 v99, v116, v117
	global_store_dwordx4 v[158:159], v[96:99], off offset:256
	global_load_dwordx4 v[96:99], v[148:149], off
	s_nop 0
	global_load_dwordx4 v[100:103], v[160:161], off
	global_load_dwordx4 v[104:107], v[160:161], off offset:16
	global_load_dwordx4 v[108:111], v[148:149], off offset:16
	global_load_dwordx4 v[116:119], v[150:151], off
	global_load_dwordx4 v[120:123], v[160:161], off offset:512
	global_load_dwordx4 v[124:127], v[160:161], off offset:528
	s_nop 0
	global_load_dwordx4 v[158:161], v[150:151], off offset:16
	s_waitcnt vmcnt(6)
	v_pk_fma_f32 v[94:95], v[94:95], v[98:99], v[102:103]
	v_pk_fma_f32 v[92:93], v[92:93], v[96:97], v[100:101]
	s_waitcnt vmcnt(4)
	v_pk_fma_f32 v[90:91], v[90:91], v[110:111], v[106:107]
	v_pk_fma_f32 v[88:89], v[88:89], v[108:109], v[104:105]
	v_pk_mul_f32 v[96:97], v[90:91], v[90:91]
	v_pk_mul_f32 v[98:99], v[88:89], v[88:89]
	s_waitcnt vmcnt(2)
	v_pk_fma_f32 v[86:87], v[86:87], v[118:119], v[122:123]
	v_pk_fma_f32 v[84:85], v[84:85], v[116:117], v[120:121]
	v_pk_fma_f32 v[96:97], v[94:95], v[94:95], v[96:97]
	v_pk_fma_f32 v[98:99], v[92:93], v[92:93], v[98:99]
	s_waitcnt vmcnt(0)
	v_pk_fma_f32 v[82:83], v[82:83], v[160:161], v[126:127]
	v_pk_fma_f32 v[80:81], v[80:81], v[158:159], v[124:125]
	v_pk_fma_f32 v[96:97], v[86:87], v[86:87], v[96:97]
	v_pk_fma_f32 v[98:99], v[84:85], v[84:85], v[98:99]
	v_pk_fma_f32 v[96:97], v[82:83], v[82:83], v[96:97]
	v_pk_fma_f32 v[98:99], v[80:81], v[80:81], v[98:99]
	v_add_f32_e32 v96, v96, v97
	v_add_f32_e32 v98, v98, v99
	v_add_f32_e32 v96, v98, v96
	ds_bpermute_b32 v97, v169, v96
	v_lshl_add_u64 v[98:99], s[30:31], 0, v[192:193]
	global_store_dwordx4 v[98:99], v[92:95], off nt
	global_store_dwordx4 v[98:99], v[88:91], off offset:16 nt
	global_store_dwordx4 v[98:99], v[84:87], off offset:512 nt
	global_store_dwordx4 v[98:99], v[80:83], off offset:528 nt
	s_waitcnt lgkmcnt(0)
	v_add_f32_e32 v96, v96, v97
	ds_bpermute_b32 v97, v170, v96
	s_and_saveexec_b64 s[12:13], s[0:1]
	s_cbranch_execz .LBB0_1046
	v_lshl_add_u64 v[98:99], v[114:115], 2, s[8:9]
	s_waitcnt lgkmcnt(0)
	v_add_f32_e32 v96, v96, v97
	global_atomic_add_f32 v[98:99], v96, off
.LBB0_1046:
	s_or_b64 exec, exec, s[12:13]
	global_load_dwordx4 v[100:103], v[152:153], off
	global_load_dwordx4 v[104:107], v[152:153], off offset:16
	global_load_dwordx4 v[108:111], v[156:157], off
	global_load_dwordx4 v[114:117], v[156:157], off offset:16
	global_load_dwordx4 v[118:121], v[146:147], off
	global_load_dwordx4 v[122:125], v[146:147], off offset:16
	global_load_dwordx4 v[158:161], v[146:147], off offset:512
	global_load_dwordx4 v[172:175], v[146:147], off offset:528
	v_or_b32_e32 v98, 48, v154
	v_ashrrev_i32_e32 v99, 31, v98
	s_waitcnt lgkmcnt(0)
	v_lshlrev_b64 v[96:97], 10, v[98:99]
	v_lshl_add_u64 v[112:113], v[112:113], 1, s[34:35]
	v_lshl_add_u64 v[96:97], v[96:97], 0, v[144:145]
	v_readlane_b32 s76, v250, 6
	v_lshlrev_b64 v[126:127], 2, v[96:97]
	v_readlane_b32 s77, v250, 7
	v_readlane_b32 s78, v250, 8
	v_readlane_b32 s79, v250, 9
	v_lshl_add_u64 v[154:155], s[76:77], 0, v[126:127]
	v_readlane_b32 s80, v250, 10
	v_readlane_b32 s81, v250, 11
	v_readlane_b32 s82, v250, 12
	v_readlane_b32 s83, v250, 13
	v_readlane_b32 s84, v250, 14
	v_readlane_b32 s85, v250, 15
	v_readlane_b32 s86, v250, 16
	v_readlane_b32 s87, v250, 17
	v_readlane_b32 s88, v250, 18
	v_readlane_b32 s89, v250, 19
	v_readlane_b32 s90, v250, 20
	v_readlane_b32 s91, v250, 21
	s_waitcnt vmcnt(7)
	v_pk_add_f32 v[102:103], v[102:103], 1.0 op_sel_hi:[1,0]
	v_pk_add_f32 v[100:101], v[100:101], 1.0 op_sel_hi:[1,0]
	s_waitcnt vmcnt(6)
	v_pk_add_f32 v[106:107], v[106:107], 1.0 op_sel_hi:[1,0]
	v_pk_add_f32 v[104:105], v[104:105], 1.0 op_sel_hi:[1,0]
	s_waitcnt vmcnt(4)
	v_pk_add_f32 v[116:117], v[116:117], 1.0 op_sel_hi:[1,0]
	v_pk_add_f32 v[114:115], v[114:115], 1.0 op_sel_hi:[1,0]
	s_waitcnt vmcnt(3)
	v_pk_mul_f32 v[94:95], v[94:95], v[120:121]
	v_pk_mul_f32 v[92:93], v[92:93], v[118:119]
	s_waitcnt vmcnt(2)
	v_pk_mul_f32 v[90:91], v[90:91], v[124:125]
	v_pk_mul_f32 v[88:89], v[88:89], v[122:123]
	s_waitcnt vmcnt(0)
	v_pk_mul_f32 v[82:83], v[82:83], v[174:175]
	v_pk_mul_f32 v[80:81], v[80:81], v[172:173]
	v_pk_add_f32 v[110:111], v[110:111], 1.0 op_sel_hi:[1,0]
	v_pk_add_f32 v[108:109], v[108:109], 1.0 op_sel_hi:[1,0]
	v_pk_mul_f32 v[86:87], v[86:87], v[160:161]
	v_pk_mul_f32 v[84:85], v[84:85], v[158:159]
	v_pk_mul_f32 v[94:95], v[102:103], v[94:95]
	v_pk_mul_f32 v[92:93], v[100:101], v[92:93]
	v_pk_mul_f32 v[90:91], v[106:107], v[90:91]
	v_pk_mul_f32 v[88:89], v[104:105], v[88:89]
	v_pk_mul_f32 v[100:101], v[116:117], v[82:83]
	v_pk_mul_f32 v[102:103], v[114:115], v[80:81]
	v_cvt_pk_bf16_f32 v80, v92, v93
	v_cvt_pk_bf16_f32 v81, v94, v95
	v_cvt_pk_bf16_f32 v82, v88, v89
	v_cvt_pk_bf16_f32 v83, v90, v91
	v_pk_mul_f32 v[86:87], v[110:111], v[86:87]
	v_pk_mul_f32 v[84:85], v[108:109], v[84:85]
	global_store_dwordx4 v[112:113], v[80:83], off
	s_nop 1
	v_cvt_pk_bf16_f32 v80, v84, v85
	v_cvt_pk_bf16_f32 v81, v86, v87
	v_cvt_pk_bf16_f32 v82, v102, v103
	v_cvt_pk_bf16_f32 v83, v100, v101
	global_store_dwordx4 v[112:113], v[80:83], off offset:256
	global_load_dwordx4 v[80:83], v[148:149], off
	s_nop 0
	global_load_dwordx4 v[84:87], v[154:155], off
	global_load_dwordx4 v[88:91], v[154:155], off offset:16
	global_load_dwordx4 v[92:95], v[148:149], off offset:16
	global_load_dwordx4 v[100:103], v[150:151], off
	global_load_dwordx4 v[104:107], v[154:155], off offset:512
	global_load_dwordx4 v[108:111], v[154:155], off offset:528
	global_load_dwordx4 v[112:115], v[150:151], off offset:16
	s_waitcnt vmcnt(6)
	v_pk_fma_f32 v[78:79], v[78:79], v[82:83], v[86:87]
	v_pk_fma_f32 v[76:77], v[76:77], v[80:81], v[84:85]
	s_waitcnt vmcnt(4)
	v_pk_fma_f32 v[74:75], v[74:75], v[94:95], v[90:91]
	v_pk_fma_f32 v[72:73], v[72:73], v[92:93], v[88:89]
	v_pk_mul_f32 v[80:81], v[74:75], v[74:75]
	v_pk_mul_f32 v[82:83], v[72:73], v[72:73]
	s_waitcnt vmcnt(2)
	v_pk_fma_f32 v[70:71], v[70:71], v[102:103], v[106:107]
	v_pk_fma_f32 v[68:69], v[68:69], v[100:101], v[104:105]
	v_pk_fma_f32 v[80:81], v[78:79], v[78:79], v[80:81]
	v_pk_fma_f32 v[82:83], v[76:77], v[76:77], v[82:83]
	s_waitcnt vmcnt(0)
	v_pk_fma_f32 v[66:67], v[66:67], v[114:115], v[110:111]
	v_pk_fma_f32 v[64:65], v[64:65], v[112:113], v[108:109]
	v_pk_fma_f32 v[80:81], v[70:71], v[70:71], v[80:81]
	v_pk_fma_f32 v[82:83], v[68:69], v[68:69], v[82:83]
	v_pk_fma_f32 v[80:81], v[66:67], v[66:67], v[80:81]
	v_pk_fma_f32 v[82:83], v[64:65], v[64:65], v[82:83]
	v_add_f32_e32 v80, v80, v81
	v_add_f32_e32 v82, v82, v83
	v_add_f32_e32 v80, v82, v80
	ds_bpermute_b32 v81, v169, v80
	v_lshl_add_u64 v[82:83], s[30:31], 0, v[126:127]
	global_store_dwordx4 v[82:83], v[76:79], off nt
	global_store_dwordx4 v[82:83], v[72:75], off offset:16 nt
	global_store_dwordx4 v[82:83], v[68:71], off offset:512 nt
	global_store_dwordx4 v[82:83], v[64:67], off offset:528 nt
	s_waitcnt lgkmcnt(0)
	v_add_f32_e32 v80, v80, v81
	ds_bpermute_b32 v81, v170, v80
	s_and_saveexec_b64 s[12:13], s[0:1]
	s_cbranch_execz .LBB0_1048
	v_lshl_add_u64 v[82:83], v[98:99], 2, s[8:9]
	s_waitcnt lgkmcnt(0)
	v_add_f32_e32 v80, v80, v81
	global_atomic_add_f32 v[82:83], v80, off
.LBB0_1048:
	s_or_b64 exec, exec, s[12:13]
	global_load_dwordx4 v[88:91], v[152:153], off
	global_load_dwordx4 v[92:95], v[152:153], off offset:16
	global_load_dwordx4 v[98:101], v[156:157], off
	global_load_dwordx4 v[102:105], v[156:157], off offset:16
	global_load_dwordx4 v[106:109], v[146:147], off
	global_load_dwordx4 v[110:113], v[146:147], off offset:16
	global_load_dwordx4 v[114:117], v[146:147], off offset:512
	global_load_dwordx4 v[118:121], v[146:147], off offset:528
	s_addk_i32 s45, 0x80
	s_ashr_i32 s12, s45, 13
	s_mulk_i32 s12, 0x1800
	v_or_b32_e32 v82, s45, v162
	s_ashr_i32 s13, s12, 31
	v_ashrrev_i32_e32 v83, 31, v82
	s_lshl_b64 s[12:13], s[12:13], 2
	s_waitcnt lgkmcnt(0)
	v_lshlrev_b64 v[80:81], 10, v[82:83]
	s_add_u32 s12, s68, s12
	v_lshl_add_u64 v[84:85], v[80:81], 0, v[144:145]
	s_addc_u32 s13, s69, s13
	v_readlane_b32 s76, v250, 6
	v_lshl_add_u64 v[96:97], v[96:97], 1, s[34:35]
	v_lshlrev_b64 v[122:123], 2, v[84:85]
	v_readlane_b32 s77, v250, 7
	v_lshl_add_u64 v[86:87], v[144:145], 2, s[12:13]
	v_add_co_u32_e32 v126, vcc, s47, v86
	v_lshl_add_u64 v[124:125], s[76:77], 0, v[122:123]
	v_lshl_add_u64 v[80:81], v[86:87], 0, s[22:23]
	v_addc_co_u32_e32 v127, vcc, 0, v87, vcc
	v_readlane_b32 s78, v250, 8
	v_readlane_b32 s79, v250, 9
	v_readlane_b32 s80, v250, 10
	v_readlane_b32 s81, v250, 11
	v_readlane_b32 s82, v250, 12
	v_readlane_b32 s83, v250, 13
	v_readlane_b32 s84, v250, 14
	v_readlane_b32 s85, v250, 15
	v_readlane_b32 s86, v250, 16
	v_readlane_b32 s87, v250, 17
	v_readlane_b32 s88, v250, 18
	v_readlane_b32 s89, v250, 19
	v_readlane_b32 s90, v250, 20
	v_readlane_b32 s91, v250, 21
	s_waitcnt vmcnt(7)
	v_pk_add_f32 v[90:91], v[90:91], 1.0 op_sel_hi:[1,0]
	v_pk_add_f32 v[88:89], v[88:89], 1.0 op_sel_hi:[1,0]
	s_waitcnt vmcnt(6)
	v_pk_add_f32 v[94:95], v[94:95], 1.0 op_sel_hi:[1,0]
	v_pk_add_f32 v[92:93], v[92:93], 1.0 op_sel_hi:[1,0]
	s_waitcnt vmcnt(4)
	v_pk_add_f32 v[104:105], v[104:105], 1.0 op_sel_hi:[1,0]
	v_pk_add_f32 v[102:103], v[102:103], 1.0 op_sel_hi:[1,0]
	s_waitcnt vmcnt(3)
	v_pk_mul_f32 v[78:79], v[78:79], v[108:109]
	v_pk_mul_f32 v[76:77], v[76:77], v[106:107]
	s_waitcnt vmcnt(2)
	v_pk_mul_f32 v[74:75], v[74:75], v[112:113]
	v_pk_mul_f32 v[72:73], v[72:73], v[110:111]
	s_waitcnt vmcnt(0)
	v_pk_mul_f32 v[66:67], v[66:67], v[120:121]
	v_pk_mul_f32 v[64:65], v[64:65], v[118:119]
	v_pk_add_f32 v[100:101], v[100:101], 1.0 op_sel_hi:[1,0]
	v_pk_add_f32 v[98:99], v[98:99], 1.0 op_sel_hi:[1,0]
	v_pk_mul_f32 v[70:71], v[70:71], v[116:117]
	v_pk_mul_f32 v[68:69], v[68:69], v[114:115]
	v_pk_mul_f32 v[78:79], v[90:91], v[78:79]
	v_pk_mul_f32 v[76:77], v[88:89], v[76:77]
	v_pk_mul_f32 v[74:75], v[94:95], v[74:75]
	v_pk_mul_f32 v[72:73], v[92:93], v[72:73]
	v_pk_mul_f32 v[88:89], v[104:105], v[66:67]
	v_pk_mul_f32 v[90:91], v[102:103], v[64:65]
	v_cvt_pk_bf16_f32 v64, v76, v77
	v_cvt_pk_bf16_f32 v65, v78, v79
	v_cvt_pk_bf16_f32 v66, v72, v73
	v_cvt_pk_bf16_f32 v67, v74, v75
	v_pk_mul_f32 v[70:71], v[100:101], v[70:71]
	v_pk_mul_f32 v[68:69], v[98:99], v[68:69]
	global_store_dwordx4 v[96:97], v[64:67], off
	s_nop 1
	v_cvt_pk_bf16_f32 v64, v68, v69
	v_cvt_pk_bf16_f32 v65, v70, v71
	v_cvt_pk_bf16_f32 v66, v90, v91
	v_cvt_pk_bf16_f32 v67, v88, v89
	global_store_dwordx4 v[96:97], v[64:67], off offset:256
	global_load_dwordx4 v[66:69], v[124:125], off offset:16
	s_nop 0
	global_load_dwordx4 v[70:73], v[124:125], off
	global_load_dwordx4 v[74:77], v[126:127], off
	global_load_dwordx4 v[88:91], v[80:81], off offset:16
	global_load_dwordx4 v[92:95], v[124:125], off offset:528
	global_load_dwordx4 v[96:99], v[124:125], off offset:512
	global_load_dwordx4 v[100:103], v[126:127], off offset:512
	v_lshl_add_u64 v[64:65], v[86:87], 0, s[24:25]
	global_load_dwordx4 v[104:107], v[64:65], off offset:16
	s_waitcnt vmcnt(5)
	v_pk_fma_f32 v[62:63], v[62:63], v[76:77], v[72:73]
	s_waitcnt vmcnt(4)
	v_pk_fma_f32 v[58:59], v[58:59], v[90:91], v[68:69]
	v_pk_fma_f32 v[56:57], v[56:57], v[88:89], v[66:67]
	v_pk_fma_f32 v[60:61], v[60:61], v[74:75], v[70:71]
	v_pk_mul_f32 v[66:67], v[58:59], v[58:59]
	v_pk_mul_f32 v[68:69], v[56:57], v[56:57]
	s_waitcnt vmcnt(1)
	v_pk_fma_f32 v[54:55], v[54:55], v[102:103], v[98:99]
	v_pk_fma_f32 v[52:53], v[52:53], v[100:101], v[96:97]
	v_pk_fma_f32 v[66:67], v[62:63], v[62:63], v[66:67]
	v_pk_fma_f32 v[68:69], v[60:61], v[60:61], v[68:69]
	s_waitcnt vmcnt(0)
	v_pk_fma_f32 v[50:51], v[50:51], v[106:107], v[94:95]
	v_pk_fma_f32 v[48:49], v[48:49], v[104:105], v[92:93]
	v_pk_fma_f32 v[66:67], v[54:55], v[54:55], v[66:67]
	v_pk_fma_f32 v[68:69], v[52:53], v[52:53], v[68:69]
	v_pk_fma_f32 v[66:67], v[50:51], v[50:51], v[66:67]
	v_pk_fma_f32 v[68:69], v[48:49], v[48:49], v[68:69]
	v_add_f32_e32 v66, v66, v67
	v_add_f32_e32 v68, v68, v69
	v_add_f32_e32 v66, v68, v66
	ds_bpermute_b32 v67, v169, v66
	v_lshl_add_u64 v[68:69], s[30:31], 0, v[122:123]
	global_store_dwordx4 v[68:69], v[60:63], off nt
	global_store_dwordx4 v[68:69], v[56:59], off offset:16 nt
	global_store_dwordx4 v[68:69], v[52:55], off offset:512 nt
	global_store_dwordx4 v[68:69], v[48:51], off offset:528 nt
	s_waitcnt lgkmcnt(0)
	v_add_f32_e32 v66, v66, v67
	ds_bpermute_b32 v67, v170, v66
	s_and_saveexec_b64 s[12:13], s[0:1]
	s_cbranch_execz .LBB0_1050
	v_lshl_add_u64 v[68:69], v[82:83], 2, s[8:9]
	s_waitcnt lgkmcnt(0)
	v_add_f32_e32 v66, v66, v67
	global_atomic_add_f32 v[68:69], v66, off
.LBB0_1050:
	s_or_b64 exec, exec, s[12:13]
	v_lshl_add_u64 v[68:69], v[86:87], 0, s[26:27]
	v_add_co_u32_e32 v70, vcc, 0x4000, v86
	global_load_dwordx4 v[74:77], v[146:147], off offset:16
	global_load_dwordx4 v[88:91], v[146:147], off
	global_load_dwordx4 v[92:95], v[146:147], off offset:528
	global_load_dwordx4 v[96:99], v[146:147], off offset:512
	s_waitcnt lgkmcnt(0)
	v_lshl_add_u64 v[66:67], v[86:87], 0, s[28:29]
	global_load_dwordx4 v[100:103], v[68:69], off offset:16
	global_load_dwordx4 v[104:107], v[66:67], off offset:16
	v_addc_co_u32_e32 v71, vcc, 0, v87, vcc
	global_load_dwordx4 v[108:111], v[70:71], off
	global_load_dwordx4 v[112:115], v[70:71], off offset:512
	v_or_b32_e32 v72, 16, v82
	v_lshl_add_u64 v[78:79], v[84:85], 1, s[34:35]
	v_ashrrev_i32_e32 v73, 31, v72
	v_lshlrev_b64 v[70:71], 10, v[72:73]
	v_lshl_add_u64 v[70:71], v[70:71], 0, v[144:145]
	v_readlane_b32 s76, v250, 6
	v_lshlrev_b64 v[116:117], 2, v[70:71]
	v_readlane_b32 s77, v250, 7
	v_readlane_b32 s78, v250, 8
	v_readlane_b32 s79, v250, 9
	v_lshl_add_u64 v[118:119], s[76:77], 0, v[116:117]
	v_readlane_b32 s80, v250, 10
	v_readlane_b32 s81, v250, 11
	v_readlane_b32 s82, v250, 12
	v_readlane_b32 s83, v250, 13
	v_readlane_b32 s84, v250, 14
	v_readlane_b32 s85, v250, 15
	v_readlane_b32 s86, v250, 16
	v_readlane_b32 s87, v250, 17
	v_readlane_b32 s88, v250, 18
	v_readlane_b32 s89, v250, 19
	v_readlane_b32 s90, v250, 20
	v_readlane_b32 s91, v250, 21
	s_waitcnt vmcnt(7)
	v_pk_mul_f32 v[58:59], v[58:59], v[76:77]
	s_waitcnt vmcnt(6)
	v_pk_mul_f32 v[62:63], v[62:63], v[90:91]
	v_pk_mul_f32 v[60:61], v[60:61], v[88:89]
	v_pk_mul_f32 v[56:57], v[56:57], v[74:75]
	s_waitcnt vmcnt(5)
	v_pk_mul_f32 v[50:51], v[50:51], v[94:95]
	v_pk_mul_f32 v[48:49], v[48:49], v[92:93]
	s_waitcnt vmcnt(3)
	v_pk_add_f32 v[74:75], v[102:103], 1.0 op_sel_hi:[1,0]
	v_pk_add_f32 v[76:77], v[100:101], 1.0 op_sel_hi:[1,0]
	s_waitcnt vmcnt(2)
	v_pk_add_f32 v[84:85], v[106:107], 1.0 op_sel_hi:[1,0]
	v_pk_add_f32 v[86:87], v[104:105], 1.0 op_sel_hi:[1,0]
	s_waitcnt vmcnt(1)
	v_pk_add_f32 v[88:89], v[110:111], 1.0 op_sel_hi:[1,0]
	v_pk_add_f32 v[90:91], v[108:109], 1.0 op_sel_hi:[1,0]
	v_pk_mul_f32 v[58:59], v[74:75], v[58:59]
	v_pk_mul_f32 v[56:57], v[76:77], v[56:57]
	v_pk_mul_f32 v[74:75], v[84:85], v[50:51]
	v_pk_mul_f32 v[76:77], v[86:87], v[48:49]
	v_pk_mul_f32 v[50:51], v[88:89], v[62:63]
	v_pk_mul_f32 v[48:49], v[90:91], v[60:61]
	v_pk_mul_f32 v[54:55], v[54:55], v[98:99]
	v_pk_mul_f32 v[52:53], v[52:53], v[96:97]
	s_waitcnt vmcnt(0)
	v_pk_add_f32 v[92:93], v[114:115], 1.0 op_sel_hi:[1,0]
	v_pk_add_f32 v[94:95], v[112:113], 1.0 op_sel_hi:[1,0]
	v_cvt_pk_bf16_f32 v48, v48, v49
	v_cvt_pk_bf16_f32 v49, v50, v51
	v_cvt_pk_bf16_f32 v50, v56, v57
	v_cvt_pk_bf16_f32 v51, v58, v59
	v_pk_mul_f32 v[54:55], v[92:93], v[54:55]
	v_pk_mul_f32 v[52:53], v[94:95], v[52:53]
	global_store_dwordx4 v[78:79], v[48:51], off
	s_nop 1
	v_cvt_pk_bf16_f32 v48, v52, v53
	v_cvt_pk_bf16_f32 v49, v54, v55
	v_cvt_pk_bf16_f32 v50, v76, v77
	v_cvt_pk_bf16_f32 v51, v74, v75
	global_store_dwordx4 v[78:79], v[48:51], off offset:256
	global_load_dwordx4 v[48:51], v[80:81], off
	s_nop 0
	global_load_dwordx4 v[52:55], v[118:119], off
	global_load_dwordx4 v[56:59], v[118:119], off offset:16
	global_load_dwordx4 v[60:63], v[80:81], off offset:16
	global_load_dwordx4 v[74:77], v[64:65], off
	global_load_dwordx4 v[84:87], v[118:119], off offset:512
	global_load_dwordx4 v[88:91], v[118:119], off offset:528
	global_load_dwordx4 v[92:95], v[64:65], off offset:16
	s_waitcnt vmcnt(6)
	v_pk_fma_f32 v[46:47], v[46:47], v[50:51], v[54:55]
	v_pk_fma_f32 v[44:45], v[44:45], v[48:49], v[52:53]
	s_waitcnt vmcnt(4)
	v_pk_fma_f32 v[42:43], v[42:43], v[62:63], v[58:59]
	v_pk_fma_f32 v[40:41], v[40:41], v[60:61], v[56:57]
	v_pk_mul_f32 v[48:49], v[42:43], v[42:43]
	v_pk_mul_f32 v[50:51], v[40:41], v[40:41]
	s_waitcnt vmcnt(2)
	v_pk_fma_f32 v[38:39], v[38:39], v[76:77], v[86:87]
	v_pk_fma_f32 v[36:37], v[36:37], v[74:75], v[84:85]
	v_pk_fma_f32 v[48:49], v[46:47], v[46:47], v[48:49]
	v_pk_fma_f32 v[50:51], v[44:45], v[44:45], v[50:51]
	s_waitcnt vmcnt(0)
	v_pk_fma_f32 v[34:35], v[34:35], v[94:95], v[90:91]
	v_pk_fma_f32 v[32:33], v[32:33], v[92:93], v[88:89]
	v_pk_fma_f32 v[48:49], v[38:39], v[38:39], v[48:49]
	v_pk_fma_f32 v[50:51], v[36:37], v[36:37], v[50:51]
	v_pk_fma_f32 v[48:49], v[34:35], v[34:35], v[48:49]
	v_pk_fma_f32 v[50:51], v[32:33], v[32:33], v[50:51]
	v_add_f32_e32 v48, v48, v49
	v_add_f32_e32 v50, v50, v51
	v_add_f32_e32 v48, v50, v48
	ds_bpermute_b32 v49, v169, v48
	v_lshl_add_u64 v[50:51], s[30:31], 0, v[116:117]
	global_store_dwordx4 v[50:51], v[44:47], off nt
	global_store_dwordx4 v[50:51], v[40:43], off offset:16 nt
	global_store_dwordx4 v[50:51], v[36:39], off offset:512 nt
	global_store_dwordx4 v[50:51], v[32:35], off offset:528 nt
	s_waitcnt lgkmcnt(0)
	v_add_f32_e32 v48, v48, v49
	ds_bpermute_b32 v49, v170, v48
	s_and_saveexec_b64 s[12:13], s[0:1]
	s_cbranch_execz .LBB0_1052
	v_lshl_add_u64 v[50:51], v[72:73], 2, s[8:9]
	s_waitcnt lgkmcnt(0)
	v_add_f32_e32 v48, v48, v49
	global_atomic_add_f32 v[50:51], v48, off
.LBB0_1052:
	s_or_b64 exec, exec, s[12:13]
	global_load_dwordx4 v[52:55], v[68:69], off
	global_load_dwordx4 v[56:59], v[68:69], off offset:16
	global_load_dwordx4 v[60:63], v[66:67], off
	global_load_dwordx4 v[72:75], v[66:67], off offset:16
	global_load_dwordx4 v[76:79], v[146:147], off
	global_load_dwordx4 v[84:87], v[146:147], off offset:16
	global_load_dwordx4 v[88:91], v[146:147], off offset:512
	global_load_dwordx4 v[92:95], v[146:147], off offset:528
	v_or_b32_e32 v50, 32, v82
	v_ashrrev_i32_e32 v51, 31, v50
	s_waitcnt lgkmcnt(0)
	v_lshlrev_b64 v[48:49], 10, v[50:51]
	v_lshl_add_u64 v[70:71], v[70:71], 1, s[34:35]
	v_lshl_add_u64 v[48:49], v[48:49], 0, v[144:145]
	v_readlane_b32 s76, v250, 6
	v_lshlrev_b64 v[96:97], 2, v[48:49]
	v_readlane_b32 s77, v250, 7
	v_readlane_b32 s78, v250, 8
	v_readlane_b32 s79, v250, 9
	v_lshl_add_u64 v[98:99], s[76:77], 0, v[96:97]
	v_readlane_b32 s80, v250, 10
	v_readlane_b32 s81, v250, 11
	v_readlane_b32 s82, v250, 12
	v_readlane_b32 s83, v250, 13
	v_readlane_b32 s84, v250, 14
	v_readlane_b32 s85, v250, 15
	v_readlane_b32 s86, v250, 16
	v_readlane_b32 s87, v250, 17
	v_readlane_b32 s88, v250, 18
	v_readlane_b32 s89, v250, 19
	v_readlane_b32 s90, v250, 20
	v_readlane_b32 s91, v250, 21
	s_waitcnt vmcnt(7)
	v_pk_add_f32 v[54:55], v[54:55], 1.0 op_sel_hi:[1,0]
	v_pk_add_f32 v[52:53], v[52:53], 1.0 op_sel_hi:[1,0]
	s_waitcnt vmcnt(6)
	v_pk_add_f32 v[58:59], v[58:59], 1.0 op_sel_hi:[1,0]
	v_pk_add_f32 v[56:57], v[56:57], 1.0 op_sel_hi:[1,0]
	s_waitcnt vmcnt(4)
	v_pk_add_f32 v[74:75], v[74:75], 1.0 op_sel_hi:[1,0]
	v_pk_add_f32 v[72:73], v[72:73], 1.0 op_sel_hi:[1,0]
	s_waitcnt vmcnt(3)
	v_pk_mul_f32 v[46:47], v[46:47], v[78:79]
	v_pk_mul_f32 v[44:45], v[44:45], v[76:77]
	s_waitcnt vmcnt(2)
	v_pk_mul_f32 v[42:43], v[42:43], v[86:87]
	v_pk_mul_f32 v[40:41], v[40:41], v[84:85]
	s_waitcnt vmcnt(0)
	v_pk_mul_f32 v[34:35], v[34:35], v[94:95]
	v_pk_mul_f32 v[32:33], v[32:33], v[92:93]
	v_pk_add_f32 v[62:63], v[62:63], 1.0 op_sel_hi:[1,0]
	v_pk_add_f32 v[60:61], v[60:61], 1.0 op_sel_hi:[1,0]
	v_pk_mul_f32 v[38:39], v[38:39], v[90:91]
	v_pk_mul_f32 v[36:37], v[36:37], v[88:89]
	v_pk_mul_f32 v[46:47], v[54:55], v[46:47]
	v_pk_mul_f32 v[44:45], v[52:53], v[44:45]
	v_pk_mul_f32 v[42:43], v[58:59], v[42:43]
	v_pk_mul_f32 v[40:41], v[56:57], v[40:41]
	v_pk_mul_f32 v[52:53], v[74:75], v[34:35]
	v_pk_mul_f32 v[54:55], v[72:73], v[32:33]
	v_cvt_pk_bf16_f32 v32, v44, v45
	v_cvt_pk_bf16_f32 v33, v46, v47
	v_cvt_pk_bf16_f32 v34, v40, v41
	v_cvt_pk_bf16_f32 v35, v42, v43
	v_pk_mul_f32 v[38:39], v[62:63], v[38:39]
	v_pk_mul_f32 v[36:37], v[60:61], v[36:37]
	global_store_dwordx4 v[70:71], v[32:35], off
	s_nop 1
	v_cvt_pk_bf16_f32 v32, v36, v37
	v_cvt_pk_bf16_f32 v33, v38, v39
	v_cvt_pk_bf16_f32 v34, v54, v55
	v_cvt_pk_bf16_f32 v35, v52, v53
	global_store_dwordx4 v[70:71], v[32:35], off offset:256
	global_load_dwordx4 v[32:35], v[80:81], off
	s_nop 0
	global_load_dwordx4 v[36:39], v[98:99], off
	global_load_dwordx4 v[40:43], v[98:99], off offset:16
	global_load_dwordx4 v[44:47], v[80:81], off offset:16
	global_load_dwordx4 v[52:55], v[64:65], off
	global_load_dwordx4 v[56:59], v[98:99], off offset:512
	global_load_dwordx4 v[60:63], v[98:99], off offset:528
	global_load_dwordx4 v[70:73], v[64:65], off offset:16
	s_waitcnt vmcnt(6)
	v_pk_fma_f32 v[30:31], v[30:31], v[34:35], v[38:39]
	v_pk_fma_f32 v[28:29], v[28:29], v[32:33], v[36:37]
	s_waitcnt vmcnt(4)
	v_pk_fma_f32 v[26:27], v[26:27], v[46:47], v[42:43]
	v_pk_fma_f32 v[24:25], v[24:25], v[44:45], v[40:41]
	v_pk_mul_f32 v[32:33], v[26:27], v[26:27]
	v_pk_mul_f32 v[34:35], v[24:25], v[24:25]
	s_waitcnt vmcnt(2)
	v_pk_fma_f32 v[22:23], v[22:23], v[54:55], v[58:59]
	v_pk_fma_f32 v[20:21], v[20:21], v[52:53], v[56:57]
	v_pk_fma_f32 v[32:33], v[30:31], v[30:31], v[32:33]
	v_pk_fma_f32 v[34:35], v[28:29], v[28:29], v[34:35]
	s_waitcnt vmcnt(0)
	v_pk_fma_f32 v[18:19], v[18:19], v[72:73], v[62:63]
	v_pk_fma_f32 v[16:17], v[16:17], v[70:71], v[60:61]
	v_pk_fma_f32 v[32:33], v[22:23], v[22:23], v[32:33]
	v_pk_fma_f32 v[34:35], v[20:21], v[20:21], v[34:35]
	v_pk_fma_f32 v[32:33], v[18:19], v[18:19], v[32:33]
	v_pk_fma_f32 v[34:35], v[16:17], v[16:17], v[34:35]
	v_add_f32_e32 v32, v32, v33
	v_add_f32_e32 v34, v34, v35
	v_add_f32_e32 v32, v34, v32
	ds_bpermute_b32 v33, v169, v32
	v_lshl_add_u64 v[34:35], s[30:31], 0, v[96:97]
	global_store_dwordx4 v[34:35], v[28:31], off nt
	global_store_dwordx4 v[34:35], v[24:27], off offset:16 nt
	global_store_dwordx4 v[34:35], v[20:23], off offset:512 nt
	global_store_dwordx4 v[34:35], v[16:19], off offset:528 nt
	s_waitcnt lgkmcnt(0)
	v_add_f32_e32 v32, v32, v33
	ds_bpermute_b32 v33, v170, v32
	s_and_saveexec_b64 s[12:13], s[0:1]
	s_cbranch_execz .LBB0_1054
	v_lshl_add_u64 v[34:35], v[50:51], 2, s[8:9]
	s_waitcnt lgkmcnt(0)
	v_add_f32_e32 v32, v32, v33
	global_atomic_add_f32 v[34:35], v32, off
.LBB0_1054:
	s_or_b64 exec, exec, s[12:13]
	global_load_dwordx4 v[36:39], v[68:69], off
	global_load_dwordx4 v[40:43], v[68:69], off offset:16
	global_load_dwordx4 v[44:47], v[66:67], off
	global_load_dwordx4 v[50:53], v[66:67], off offset:16
	global_load_dwordx4 v[54:57], v[146:147], off
	global_load_dwordx4 v[58:61], v[146:147], off offset:16
	global_load_dwordx4 v[70:73], v[146:147], off offset:512
	global_load_dwordx4 v[74:77], v[146:147], off offset:528
	v_or_b32_e32 v34, 48, v82
	v_ashrrev_i32_e32 v35, 31, v34
	s_waitcnt lgkmcnt(0)
	v_lshlrev_b64 v[32:33], 10, v[34:35]
	v_lshl_add_u64 v[48:49], v[48:49], 1, s[34:35]
	v_lshl_add_u64 v[32:33], v[32:33], 0, v[144:145]
	v_readlane_b32 s76, v250, 6
	v_lshlrev_b64 v[62:63], 2, v[32:33]
	v_readlane_b32 s77, v250, 7
	v_readlane_b32 s78, v250, 8
	v_readlane_b32 s79, v250, 9
	v_lshl_add_u64 v[78:79], s[76:77], 0, v[62:63]
	v_readlane_b32 s80, v250, 10
	v_readlane_b32 s81, v250, 11
	v_readlane_b32 s82, v250, 12
	v_readlane_b32 s83, v250, 13
	v_readlane_b32 s84, v250, 14
	v_readlane_b32 s85, v250, 15
	v_readlane_b32 s86, v250, 16
	v_readlane_b32 s87, v250, 17
	v_readlane_b32 s88, v250, 18
	v_readlane_b32 s89, v250, 19
	v_readlane_b32 s90, v250, 20
	v_readlane_b32 s91, v250, 21
	s_waitcnt vmcnt(7)
	v_pk_add_f32 v[38:39], v[38:39], 1.0 op_sel_hi:[1,0]
	v_pk_add_f32 v[36:37], v[36:37], 1.0 op_sel_hi:[1,0]
	s_waitcnt vmcnt(6)
	v_pk_add_f32 v[42:43], v[42:43], 1.0 op_sel_hi:[1,0]
	v_pk_add_f32 v[40:41], v[40:41], 1.0 op_sel_hi:[1,0]
	s_waitcnt vmcnt(4)
	v_pk_add_f32 v[52:53], v[52:53], 1.0 op_sel_hi:[1,0]
	v_pk_add_f32 v[50:51], v[50:51], 1.0 op_sel_hi:[1,0]
	s_waitcnt vmcnt(3)
	v_pk_mul_f32 v[30:31], v[30:31], v[56:57]
	v_pk_mul_f32 v[28:29], v[28:29], v[54:55]
	s_waitcnt vmcnt(2)
	v_pk_mul_f32 v[26:27], v[26:27], v[60:61]
	v_pk_mul_f32 v[24:25], v[24:25], v[58:59]
	s_waitcnt vmcnt(0)
	v_pk_mul_f32 v[18:19], v[18:19], v[76:77]
	v_pk_mul_f32 v[16:17], v[16:17], v[74:75]
	v_pk_add_f32 v[46:47], v[46:47], 1.0 op_sel_hi:[1,0]
	v_pk_add_f32 v[44:45], v[44:45], 1.0 op_sel_hi:[1,0]
	v_pk_mul_f32 v[22:23], v[22:23], v[72:73]
	v_pk_mul_f32 v[20:21], v[20:21], v[70:71]
	v_pk_mul_f32 v[30:31], v[38:39], v[30:31]
	v_pk_mul_f32 v[28:29], v[36:37], v[28:29]
	v_pk_mul_f32 v[26:27], v[42:43], v[26:27]
	v_pk_mul_f32 v[24:25], v[40:41], v[24:25]
	v_pk_mul_f32 v[36:37], v[52:53], v[18:19]
	v_pk_mul_f32 v[38:39], v[50:51], v[16:17]
	v_cvt_pk_bf16_f32 v16, v28, v29
	v_cvt_pk_bf16_f32 v17, v30, v31
	v_cvt_pk_bf16_f32 v18, v24, v25
	v_cvt_pk_bf16_f32 v19, v26, v27
	v_pk_mul_f32 v[22:23], v[46:47], v[22:23]
	v_pk_mul_f32 v[20:21], v[44:45], v[20:21]
	global_store_dwordx4 v[48:49], v[16:19], off
	s_nop 1
	v_cvt_pk_bf16_f32 v16, v20, v21
	v_cvt_pk_bf16_f32 v17, v22, v23
	v_cvt_pk_bf16_f32 v18, v38, v39
	v_cvt_pk_bf16_f32 v19, v36, v37
	global_store_dwordx4 v[48:49], v[16:19], off offset:256
	global_load_dwordx4 v[16:19], v[80:81], off
	s_nop 0
	global_load_dwordx4 v[20:23], v[78:79], off
	global_load_dwordx4 v[24:27], v[78:79], off offset:16
	global_load_dwordx4 v[28:31], v[80:81], off offset:16
	global_load_dwordx4 v[36:39], v[64:65], off
	global_load_dwordx4 v[40:43], v[78:79], off offset:512
	global_load_dwordx4 v[44:47], v[78:79], off offset:528
	global_load_dwordx4 v[48:51], v[64:65], off offset:16
	s_waitcnt vmcnt(6)
	v_pk_fma_f32 v[14:15], v[14:15], v[18:19], v[22:23]
	v_pk_fma_f32 v[12:13], v[12:13], v[16:17], v[20:21]
	s_waitcnt vmcnt(4)
	v_pk_fma_f32 v[10:11], v[10:11], v[30:31], v[26:27]
	v_pk_fma_f32 v[8:9], v[8:9], v[28:29], v[24:25]
	v_pk_mul_f32 v[16:17], v[10:11], v[10:11]
	v_pk_mul_f32 v[18:19], v[8:9], v[8:9]
	s_waitcnt vmcnt(2)
	v_pk_fma_f32 v[6:7], v[6:7], v[38:39], v[42:43]
	v_pk_fma_f32 v[4:5], v[4:5], v[36:37], v[40:41]
	v_pk_fma_f32 v[16:17], v[14:15], v[14:15], v[16:17]
	v_pk_fma_f32 v[18:19], v[12:13], v[12:13], v[18:19]
	s_waitcnt vmcnt(0)
	v_pk_fma_f32 v[2:3], v[2:3], v[50:51], v[46:47]
	v_pk_fma_f32 v[0:1], v[0:1], v[48:49], v[44:45]
	v_pk_fma_f32 v[16:17], v[6:7], v[6:7], v[16:17]
	v_pk_fma_f32 v[18:19], v[4:5], v[4:5], v[18:19]
	v_pk_fma_f32 v[16:17], v[2:3], v[2:3], v[16:17]
	v_pk_fma_f32 v[18:19], v[0:1], v[0:1], v[18:19]
	v_add_f32_e32 v16, v16, v17
	v_add_f32_e32 v18, v18, v19
	v_add_f32_e32 v16, v18, v16
	ds_bpermute_b32 v17, v169, v16
	v_lshl_add_u64 v[18:19], s[30:31], 0, v[62:63]
	global_store_dwordx4 v[18:19], v[12:15], off nt
	global_store_dwordx4 v[18:19], v[8:11], off offset:16 nt
	global_store_dwordx4 v[18:19], v[4:7], off offset:512 nt
	global_store_dwordx4 v[18:19], v[0:3], off offset:528 nt
	s_waitcnt lgkmcnt(0)
	v_add_f32_e32 v16, v16, v17
	ds_bpermute_b32 v17, v170, v16
	s_and_saveexec_b64 s[12:13], s[0:1]
	s_cbranch_execz .LBB0_1056
	v_lshl_add_u64 v[18:19], v[34:35], 2, s[8:9]
	s_waitcnt lgkmcnt(0)
	v_add_f32_e32 v16, v16, v17
	global_atomic_add_f32 v[18:19], v16, off

.LBB0_1206:
	s_lshl_b32 s16, s46, 8
	s_add_i32 s16, s16, s36
	s_ashr_i32 s17, s16, 13
	s_mul_i32 s18, s17, 0x1800
	s_ashr_i32 s19, s18, 31
	v_lshl_or_b32 v144, s47, 8, v152
	v_or_b32_e32 v148, s16, v150
	s_lshl_b64 s[18:19], s[18:19], 2
	v_ashrrev_i32_e32 v145, 31, v144
	v_ashrrev_i32_e32 v149, 31, v148
	s_add_u32 s18, s29, s18
	s_addc_u32 s19, s35, s19
	v_lshlrev_b64 v[144:145], 2, v[144:145]
	v_lshlrev_b64 v[156:157], 12, v[148:149]
	v_lshl_add_u64 v[146:147], s[18:19], 0, v[144:145]
	v_lshl_add_u64 v[156:157], s[30:31], 0, v[156:157]
	v_lshl_add_u64 v[188:189], v[156:157], 0, v[144:145]
	global_load_dwordx4 v[156:159], v[146:147], off
	global_load_dwordx4 v[160:163], v[188:189], off
	global_load_dwordx4 v[164:167], v[188:189], off offset:16
	global_load_dwordx4 v[168:171], v[146:147], off offset:16
	global_load_dwordx4 v[172:175], v[146:147], off offset:512
	global_load_dwordx4 v[176:179], v[188:189], off offset:512
	global_load_dwordx4 v[180:183], v[188:189], off offset:528
	global_load_dwordx4 v[184:187], v[146:147], off offset:528
	v_or_b32_e32 v190, 16, v148
	v_ashrrev_i32_e32 v191, 31, v190
	v_lshlrev_b64 v[190:191], 12, v[190:191]
	v_lshl_add_u64 v[190:191], s[30:31], 0, v[190:191]
	v_lshl_add_u64 v[190:191], v[190:191], 0, v[144:145]
	s_addk_i32 s16, 0x80
	s_waitcnt vmcnt(0)
	v_pk_fma_f32 v[126:127], v[126:127], v[158:159], v[162:163]
	v_pk_fma_f32 v[124:125], v[124:125], v[156:157], v[160:161]
	v_pk_fma_f32 v[122:123], v[122:123], v[170:171], v[166:167]
	v_pk_fma_f32 v[120:121], v[120:121], v[168:169], v[164:165]
	v_pk_fma_f32 v[118:119], v[118:119], v[174:175], v[178:179]
	v_pk_fma_f32 v[116:117], v[116:117], v[172:173], v[176:177]
	v_pk_fma_f32 v[114:115], v[114:115], v[186:187], v[182:183]
	v_pk_fma_f32 v[112:113], v[112:113], v[184:185], v[180:181]
	global_store_dwordx4 v[188:189], v[124:127], off nt
	global_store_dwordx4 v[188:189], v[120:123], off offset:16 nt
	global_store_dwordx4 v[188:189], v[116:119], off offset:512 nt
	global_store_dwordx4 v[188:189], v[112:115], off offset:528 nt
	global_load_dwordx4 v[112:115], v[146:147], off
	s_nop 0
	global_load_dwordx4 v[116:119], v[190:191], off
	global_load_dwordx4 v[120:123], v[190:191], off offset:16
	global_load_dwordx4 v[124:127], v[146:147], off offset:16
	global_load_dwordx4 v[156:159], v[146:147], off offset:512
	global_load_dwordx4 v[160:163], v[190:191], off offset:512
	global_load_dwordx4 v[164:167], v[190:191], off offset:528
	global_load_dwordx4 v[168:171], v[146:147], off offset:528
	v_or_b32_e32 v172, 32, v148
	v_ashrrev_i32_e32 v173, 31, v172
	v_lshlrev_b64 v[172:173], 12, v[172:173]
	v_lshl_add_u64 v[172:173], s[30:31], 0, v[172:173]
	v_lshl_add_u64 v[172:173], v[172:173], 0, v[144:145]
	v_or_b32_e32 v148, 48, v148
	v_ashrrev_i32_e32 v149, 31, v148
	v_lshlrev_b64 v[148:149], 12, v[148:149]
	v_lshl_add_u64 v[148:149], s[30:31], 0, v[148:149]
	v_lshl_add_u64 v[148:149], v[148:149], 0, v[144:145]
	s_waitcnt vmcnt(6)
	v_pk_fma_f32 v[110:111], v[110:111], v[114:115], v[118:119]
	v_pk_fma_f32 v[108:109], v[108:109], v[112:113], v[116:117]
	s_waitcnt vmcnt(4)
	v_pk_fma_f32 v[106:107], v[106:107], v[126:127], v[122:123]
	v_pk_fma_f32 v[104:105], v[104:105], v[124:125], v[120:121]
	s_waitcnt vmcnt(2)
	v_pk_fma_f32 v[102:103], v[102:103], v[158:159], v[162:163]
	v_pk_fma_f32 v[100:101], v[100:101], v[156:157], v[160:161]
	s_waitcnt vmcnt(0)
	v_pk_fma_f32 v[98:99], v[98:99], v[170:171], v[166:167]
	v_pk_fma_f32 v[96:97], v[96:97], v[168:169], v[164:165]
	global_store_dwordx4 v[190:191], v[108:111], off nt
	global_store_dwordx4 v[190:191], v[104:107], off offset:16 nt
	global_store_dwordx4 v[190:191], v[100:103], off offset:512 nt
	global_store_dwordx4 v[190:191], v[96:99], off offset:528 nt
	global_load_dwordx4 v[96:99], v[146:147], off
	s_nop 0
	global_load_dwordx4 v[100:103], v[172:173], off
	global_load_dwordx4 v[104:107], v[172:173], off offset:16
	global_load_dwordx4 v[108:111], v[146:147], off offset:16
	global_load_dwordx4 v[112:115], v[146:147], off offset:512
	global_load_dwordx4 v[116:119], v[172:173], off offset:512
	global_load_dwordx4 v[120:123], v[172:173], off offset:528
	global_load_dwordx4 v[124:127], v[146:147], off offset:528
	s_waitcnt vmcnt(6)
	v_pk_fma_f32 v[94:95], v[94:95], v[98:99], v[102:103]
	v_pk_fma_f32 v[92:93], v[92:93], v[96:97], v[100:101]
	s_waitcnt vmcnt(4)
	v_pk_fma_f32 v[90:91], v[90:91], v[110:111], v[106:107]
	v_pk_fma_f32 v[88:89], v[88:89], v[108:109], v[104:105]
	s_waitcnt vmcnt(2)
	v_pk_fma_f32 v[86:87], v[86:87], v[114:115], v[118:119]
	v_pk_fma_f32 v[84:85], v[84:85], v[112:113], v[116:117]
	s_waitcnt vmcnt(0)
	v_pk_fma_f32 v[82:83], v[82:83], v[126:127], v[122:123]
	v_pk_fma_f32 v[80:81], v[80:81], v[124:125], v[120:121]
	global_store_dwordx4 v[172:173], v[92:95], off nt
	global_store_dwordx4 v[172:173], v[88:91], off offset:16 nt
	global_store_dwordx4 v[172:173], v[84:87], off offset:512 nt
	global_store_dwordx4 v[172:173], v[80:83], off offset:528 nt
	global_load_dwordx4 v[84:87], v[146:147], off
	s_nop 0
	global_load_dwordx4 v[88:91], v[148:149], off
	global_load_dwordx4 v[92:95], v[148:149], off offset:16
	global_load_dwordx4 v[96:99], v[146:147], off offset:16
	global_load_dwordx4 v[100:103], v[146:147], off offset:512
	global_load_dwordx4 v[104:107], v[148:149], off offset:512
	global_load_dwordx4 v[108:111], v[148:149], off offset:528
	global_load_dwordx4 v[112:115], v[146:147], off offset:528
	v_or_b32_e32 v82, s16, v150
	s_ashr_i32 s16, s16, 13
	s_mulk_i32 s16, 0x1800
	s_ashr_i32 s17, s16, 31
	v_ashrrev_i32_e32 v83, 31, v82
	s_lshl_b64 s[16:17], s[16:17], 2
	v_lshlrev_b64 v[80:81], 12, v[82:83]
	s_add_u32 s16, s29, s16
	v_lshl_add_u64 v[80:81], s[30:31], 0, v[80:81]
	s_addc_u32 s17, s35, s17
	v_lshl_add_u64 v[116:117], v[80:81], 0, v[144:145]
	v_lshl_add_u64 v[80:81], s[16:17], 0, v[144:145]
	s_and_b64 vcc, exec, s[0:1]
	s_mov_b64 s[0:1], -1
	s_waitcnt vmcnt(6)
	v_pk_fma_f32 v[78:79], v[78:79], v[86:87], v[90:91]
	v_pk_fma_f32 v[76:77], v[76:77], v[84:85], v[88:89]
	s_waitcnt vmcnt(4)
	v_pk_fma_f32 v[74:75], v[74:75], v[98:99], v[94:95]
	v_pk_fma_f32 v[72:73], v[72:73], v[96:97], v[92:93]
	s_waitcnt vmcnt(2)
	v_pk_fma_f32 v[70:71], v[70:71], v[102:103], v[106:107]
	v_pk_fma_f32 v[68:69], v[68:69], v[100:101], v[104:105]
	s_waitcnt vmcnt(0)
	v_pk_fma_f32 v[66:67], v[66:67], v[114:115], v[110:111]
	v_pk_fma_f32 v[64:65], v[64:65], v[112:113], v[108:109]
	global_store_dwordx4 v[148:149], v[76:79], off nt
	global_store_dwordx4 v[148:149], v[72:75], off offset:16 nt
	global_store_dwordx4 v[148:149], v[68:71], off offset:512 nt
	global_store_dwordx4 v[148:149], v[64:67], off offset:528 nt
	global_load_dwordx4 v[64:67], v[80:81], off
	s_nop 0
	global_load_dwordx4 v[68:71], v[116:117], off
	global_load_dwordx4 v[72:75], v[116:117], off offset:16
	global_load_dwordx4 v[76:79], v[80:81], off offset:16
	global_load_dwordx4 v[84:87], v[80:81], off offset:512
	global_load_dwordx4 v[88:91], v[116:117], off offset:512
	global_load_dwordx4 v[92:95], v[116:117], off offset:528
	global_load_dwordx4 v[96:99], v[80:81], off offset:528
	v_or_b32_e32 v100, 16, v82
	v_ashrrev_i32_e32 v101, 31, v100
	v_lshlrev_b64 v[100:101], 12, v[100:101]
	v_lshl_add_u64 v[100:101], s[30:31], 0, v[100:101]
	v_lshl_add_u64 v[100:101], v[100:101], 0, v[144:145]
	s_waitcnt vmcnt(6)
	v_pk_fma_f32 v[62:63], v[62:63], v[66:67], v[70:71]
	v_pk_fma_f32 v[60:61], v[60:61], v[64:65], v[68:69]
	s_waitcnt vmcnt(4)
	v_pk_fma_f32 v[58:59], v[58:59], v[78:79], v[74:75]
	v_pk_fma_f32 v[56:57], v[56:57], v[76:77], v[72:73]
	s_waitcnt vmcnt(2)
	v_pk_fma_f32 v[54:55], v[54:55], v[86:87], v[90:91]
	v_pk_fma_f32 v[52:53], v[52:53], v[84:85], v[88:89]
	s_waitcnt vmcnt(0)
	v_pk_fma_f32 v[50:51], v[50:51], v[98:99], v[94:95]
	v_pk_fma_f32 v[48:49], v[48:49], v[96:97], v[92:93]
	global_store_dwordx4 v[116:117], v[60:63], off nt
	global_store_dwordx4 v[116:117], v[56:59], off offset:16 nt
	global_store_dwordx4 v[116:117], v[52:55], off offset:512 nt
	global_store_dwordx4 v[116:117], v[48:51], off offset:528 nt
	global_load_dwordx4 v[48:51], v[80:81], off
	s_nop 0
	global_load_dwordx4 v[52:55], v[100:101], off
	global_load_dwordx4 v[56:59], v[100:101], off offset:16
	global_load_dwordx4 v[60:63], v[80:81], off offset:16
	global_load_dwordx4 v[64:67], v[80:81], off offset:512
	global_load_dwordx4 v[68:71], v[100:101], off offset:512
	global_load_dwordx4 v[72:75], v[100:101], off offset:528
	global_load_dwordx4 v[76:79], v[80:81], off offset:528
	v_or_b32_e32 v84, 32, v82
	v_ashrrev_i32_e32 v85, 31, v84
	v_lshlrev_b64 v[84:85], 12, v[84:85]
	v_lshl_add_u64 v[84:85], s[30:31], 0, v[84:85]
	v_lshl_add_u64 v[84:85], v[84:85], 0, v[144:145]
	s_waitcnt vmcnt(6)
	v_pk_fma_f32 v[46:47], v[46:47], v[50:51], v[54:55]
	v_pk_fma_f32 v[44:45], v[44:45], v[48:49], v[52:53]
	s_waitcnt vmcnt(4)
	v_pk_fma_f32 v[42:43], v[42:43], v[62:63], v[58:59]
	v_pk_fma_f32 v[40:41], v[40:41], v[60:61], v[56:57]
	s_waitcnt vmcnt(2)
	v_pk_fma_f32 v[38:39], v[38:39], v[66:67], v[70:71]
	v_pk_fma_f32 v[36:37], v[36:37], v[64:65], v[68:69]
	s_waitcnt vmcnt(0)
	v_pk_fma_f32 v[34:35], v[34:35], v[78:79], v[74:75]
	v_pk_fma_f32 v[32:33], v[32:33], v[76:77], v[72:73]
	global_store_dwordx4 v[100:101], v[44:47], off nt
	global_store_dwordx4 v[100:101], v[40:43], off offset:16 nt
	global_store_dwordx4 v[100:101], v[36:39], off offset:512 nt
	global_store_dwordx4 v[100:101], v[32:35], off offset:528 nt
	global_load_dwordx4 v[32:35], v[80:81], off
	s_nop 0
	global_load_dwordx4 v[36:39], v[84:85], off
	global_load_dwordx4 v[40:43], v[84:85], off offset:16
	global_load_dwordx4 v[44:47], v[80:81], off offset:16
	global_load_dwordx4 v[48:51], v[80:81], off offset:512
	global_load_dwordx4 v[52:55], v[84:85], off offset:512
	global_load_dwordx4 v[56:59], v[84:85], off offset:528
	global_load_dwordx4 v[60:63], v[80:81], off offset:528
	v_or_b32_e32 v64, 48, v82
	v_ashrrev_i32_e32 v65, 31, v64
	v_lshlrev_b64 v[64:65], 12, v[64:65]
	v_lshl_add_u64 v[64:65], s[30:31], 0, v[64:65]
	v_lshl_add_u64 v[64:65], v[64:65], 0, v[144:145]
	s_waitcnt vmcnt(6)
	v_pk_fma_f32 v[30:31], v[30:31], v[34:35], v[38:39]
	v_pk_fma_f32 v[28:29], v[28:29], v[32:33], v[36:37]
	s_waitcnt vmcnt(4)
	v_pk_fma_f32 v[26:27], v[26:27], v[46:47], v[42:43]
	v_pk_fma_f32 v[24:25], v[24:25], v[44:45], v[40:41]
	s_waitcnt vmcnt(2)
	v_pk_fma_f32 v[22:23], v[22:23], v[50:51], v[54:55]
	v_pk_fma_f32 v[20:21], v[20:21], v[48:49], v[52:53]
	s_waitcnt vmcnt(0)
	v_pk_fma_f32 v[18:19], v[18:19], v[62:63], v[58:59]
	v_pk_fma_f32 v[16:17], v[16:17], v[60:61], v[56:57]
	global_store_dwordx4 v[84:85], v[28:31], off nt
	global_store_dwordx4 v[84:85], v[24:27], off offset:16 nt
	global_store_dwordx4 v[84:85], v[20:23], off offset:512 nt
	global_store_dwordx4 v[84:85], v[16:19], off offset:528 nt
	global_load_dwordx4 v[16:19], v[80:81], off
	s_nop 0
	global_load_dwordx4 v[20:23], v[64:65], off
	global_load_dwordx4 v[24:27], v[64:65], off offset:16
	global_load_dwordx4 v[28:31], v[80:81], off offset:16
	global_load_dwordx4 v[32:35], v[80:81], off offset:512
	global_load_dwordx4 v[36:39], v[64:65], off offset:512
	global_load_dwordx4 v[40:43], v[64:65], off offset:528
	global_load_dwordx4 v[44:47], v[80:81], off offset:528
	s_waitcnt vmcnt(6)
	v_pk_fma_f32 v[14:15], v[14:15], v[18:19], v[22:23]
	v_pk_fma_f32 v[12:13], v[12:13], v[16:17], v[20:21]
	s_waitcnt vmcnt(4)
	v_pk_fma_f32 v[10:11], v[10:11], v[30:31], v[26:27]
	v_pk_fma_f32 v[8:9], v[8:9], v[28:29], v[24:25]
	s_waitcnt vmcnt(2)
	v_pk_fma_f32 v[6:7], v[6:7], v[34:35], v[38:39]
	v_pk_fma_f32 v[4:5], v[4:5], v[32:33], v[36:37]
	s_waitcnt vmcnt(0)
	v_pk_fma_f32 v[2:3], v[2:3], v[46:47], v[42:43]
	v_pk_fma_f32 v[0:1], v[0:1], v[44:45], v[40:41]
	global_store_dwordx4 v[64:65], v[12:15], off nt
	global_store_dwordx4 v[64:65], v[8:11], off offset:16 nt
	global_store_dwordx4 v[64:65], v[4:7], off offset:512 nt
	global_store_dwordx4 v[64:65], v[0:3], off offset:528 nt
	s_cbranch_vccnz .LBB0_1191
	s_andn2_b64 vcc, exec, s[8:9]
	s_cbranch_vccnz .LBB0_1190
	s_barrier
	s_branch .LBB0_1190
